# LayerNorm wave sums (prompt conv LN, LN phases +8/+9): six ds_bpermute hops replaced by six DPP adds + readlane broadcast
# speedup vs baseline: 1.0048x; 1.0048x over previous
.LBB0_635:
	ds_read_b128 v[14:17], v40
	ds_read_b128 v[10:13], v40 offset:16
	ds_read_b128 v[6:9], v40 offset:2048
	s_waitcnt lgkmcnt(2)
	v_mov_b32_e32 v2, v15
	v_mov_b32_e32 v3, v16
	v_mov_b32_e32 v4, v14
	v_mov_b32_e32 v5, v17
	v_pk_add_f32 v[2:3], v[2:3], v[4:5]
	s_waitcnt lgkmcnt(1)
	v_mov_b32_e32 v4, v10
	v_add_f32_e32 v2, v2, v3
	v_add_f32_e32 v28, 0, v2
	v_mov_b32_e32 v2, v11
	v_mov_b32_e32 v3, v12
	v_mov_b32_e32 v5, v13
	v_pk_add_f32 v[2:3], v[2:3], v[4:5]
	s_nop 0
	v_pk_add_f32 v[30:31], v[2:3], v[2:3] op_sel:[0,1] op_sel_hi:[1,0]
	ds_read_b128 v[2:5], v40 offset:2064
	s_waitcnt lgkmcnt(1)
	v_add_f32_e32 v32, v6, v7
	v_add_f32_e32 v42, v8, v9
	v_add_u32_e32 v40, 0x8000, v40
	s_waitcnt lgkmcnt(0)
	v_mov_b32_e32 v29, v2
	v_mov_b32_e32 v31, v3
	v_mov_b32_e32 v33, v4
	v_mov_b32_e32 v43, v5
	v_pk_add_f32 v[28:29], v[28:29], v[30:31]
	v_pk_add_f32 v[30:31], v[32:33], v[42:43]
	s_nop 0
	v_pk_add_f32 v[28:29], v[28:29], v[30:31]
	s_nop 0
	v_add_f32_e32 v26, v28, v29
	s_waitcnt lgkmcnt(0)
	s_nop 1
	v_add_f32_dpp v26, v26, v26 quad_perm:[1,0,3,2] row_mask:0xf bank_mask:0xf
	s_nop 1
	v_add_f32_dpp v26, v26, v26 quad_perm:[2,3,0,1] row_mask:0xf bank_mask:0xf
	s_nop 1
	v_add_f32_dpp v26, v26, v26 row_half_mirror row_mask:0xf bank_mask:0xf
	s_nop 1
	v_add_f32_dpp v26, v26, v26 row_mirror row_mask:0xf bank_mask:0xf
	s_nop 1
	v_add_f32_dpp v26, v26, v26 row_bcast:15 row_mask:0xa bank_mask:0xf
	s_nop 1
	v_add_f32_dpp v26, v26, v26 row_bcast:31 row_mask:0xc bank_mask:0xf
	s_nop 1
	v_readlane_b32 s100, v26, 63
	v_mov_b32_e32 v26, s100
	v_fmamk_f32 v33, v26, 0xba800000, v15
	v_fmamk_f32 v32, v26, 0xba800000, v14
	v_fmamk_f32 v17, v26, 0xba800000, v17
	v_fmac_f32_e32 v16, 0xba800000, v26
	v_pk_mul_f32 v[14:15], v[16:17], v[16:17]
	v_pk_mul_f32 v[28:29], v[32:33], v[32:33]
	v_fmamk_f32 v13, v26, 0xba800000, v13
	v_pk_mov_b32 v[30:31], v[28:29], v[14:15] op_sel:[1,0]
	v_mov_b32_e32 v29, v15
	v_pk_add_f32 v[14:15], v[30:31], v[28:29]
	v_fmamk_f32 v31, v26, 0xba800000, v11
	v_fmamk_f32 v30, v26, 0xba800000, v10
	v_fmac_f32_e32 v12, 0xba800000, v26
	v_pk_add_f32 v[28:29], v[14:15], v[14:15] op_sel_hi:[0,1]
	v_pk_mul_f32 v[10:11], v[12:13], v[12:13]
	v_pk_mul_f32 v[14:15], v[30:31], v[30:31]
	v_fmac_f32_e32 v8, 0xba800000, v26
	v_pk_mov_b32 v[42:43], v[14:15], v[10:11] op_sel:[1,0]
	v_mov_b32_e32 v15, v11
	v_pk_add_f32 v[10:11], v[42:43], v[14:15]
	v_fmamk_f32 v14, v26, 0xba800000, v6
	v_fmamk_f32 v15, v26, 0xba800000, v7
	v_mul_f32_e32 v6, v14, v14
	v_pk_fma_f32 v[6:7], v[14:15], v[14:15], v[6:7] op_sel_hi:[1,1,0]
	v_fmamk_f32 v9, v26, 0xba800000, v9
	v_mul_f32_e32 v6, v8, v8
	v_pk_add_f32 v[42:43], v[10:11], v[10:11] op_sel_hi:[0,1]
	v_pk_fma_f32 v[44:45], v[8:9], v[8:9], v[6:7] op_sel_hi:[1,1,0]
	v_fmamk_f32 v11, v26, 0xba800000, v5
	v_fmamk_f32 v10, v26, 0xba800000, v4
	v_fmamk_f32 v3, v26, 0xba800000, v3
	v_fmac_f32_e32 v2, 0xba800000, v26
	v_mul_f32_e32 v6, v2, v2
	v_mul_f32_e32 v44, v3, v3
	v_mul_f32_e32 v28, v10, v10
	v_mul_f32_e32 v42, v11, v11
	v_pk_add_f32 v[4:5], v[6:7], v[44:45]
	v_pk_add_f32 v[6:7], v[28:29], v[42:43]
	s_nop 0
	v_pk_add_f32 v[4:5], v[4:5], v[6:7]
	s_nop 0
	v_add_f32_e32 v4, v4, v5
	s_waitcnt lgkmcnt(0)
	s_nop 1
	v_add_f32_dpp v4, v4, v4 quad_perm:[1,0,3,2] row_mask:0xf bank_mask:0xf
	s_nop 1
	v_add_f32_dpp v4, v4, v4 quad_perm:[2,3,0,1] row_mask:0xf bank_mask:0xf
	s_nop 1
	v_add_f32_dpp v4, v4, v4 row_half_mirror row_mask:0xf bank_mask:0xf
	s_nop 1
	v_add_f32_dpp v4, v4, v4 row_mirror row_mask:0xf bank_mask:0xf
	s_nop 1
	v_add_f32_dpp v4, v4, v4 row_bcast:15 row_mask:0xa bank_mask:0xf
	s_nop 1
	v_add_f32_dpp v4, v4, v4 row_bcast:31 row_mask:0xc bank_mask:0xf
	s_nop 1
	v_readlane_b32 s100, v4, 63
	v_mov_b32_e32 v4, s100
	v_fmamk_f32 v4, v4, 0x3a800000, v171
	v_cmp_gt_f32_e32 vcc, s9, v4
	v_mul_f32_e32 v5, 0x4f800000, v4
	s_nop 0
	v_cndmask_b32_e32 v4, v4, v5, vcc
	v_sqrt_f32_e32 v5, v4
	s_nop 0
	v_add_u32_e32 v6, -1, v5
	v_fma_f32 v7, -v6, v5, v4
	v_cmp_ge_f32_e64 s[0:1], 0, v7
	v_add_u32_e32 v7, 1, v5
	s_nop 0
	v_cndmask_b32_e64 v6, v5, v6, s[0:1]
	v_fma_f32 v5, -v7, v5, v4
	v_cmp_lt_f32_e64 s[0:1], 0, v5
	s_nop 1
	v_cndmask_b32_e64 v5, v6, v7, s[0:1]
	v_mul_f32_e32 v6, 0x37800000, v5
	v_cndmask_b32_e32 v5, v5, v6, vcc
	v_cmp_class_f32_e32 vcc, v4, v200
	s_nop 1
	v_cndmask_b32_e32 v4, v5, v4, vcc
	v_div_scale_f32 v5, s[0:1], v4, v4, 1.0
	v_rcp_f32_e32 v6, v5
	s_mov_b32 s0, 0x19b03000
	v_fma_f32 v7, -v5, v6, 1.0
	v_fmac_f32_e32 v6, v7, v6
	v_div_scale_f32 v7, vcc, 1.0, v4, 1.0
	v_mul_f32_e32 v26, v7, v6
	v_fma_f32 v28, -v5, v26, v7
	v_fmac_f32_e32 v26, v28, v6
	v_fma_f32 v5, -v5, v26, v7
	v_div_fmas_f32 v5, v5, v6, v26
	v_div_fixup_f32 v26, v5, v4, 1.0
	flat_load_dwordx4 v[4:7], v[22:23]
	flat_load_dwordx4 v[42:45], v[22:23] offset:16
	flat_load_dwordx4 v[46:49], v[24:25]
	flat_load_dwordx4 v[50:53], v[24:25] offset:16
	v_lshl_add_u64 v[28:29], s[14:15], 0, v[20:21]
	v_add_co_u32_e32 v28, vcc, s0, v28
	v_pk_mul_f32 v[32:33], v[32:33], v[26:27] op_sel_hi:[1,0]
	s_nop 0
	v_addc_co_u32_e32 v29, vcc, 0, v29, vcc
	global_load_dwordx4 v[54:57], v[28:29], off offset:2048
	global_load_dwordx4 v[214:217], v[22:23], off offset:2048
	global_load_dwordx4 v[218:221], v[22:23], off offset:2064
	global_load_dwordx4 v[222:225], v[24:25], off offset:2048
	global_load_dwordx4 v[226:229], v[24:25], off offset:2064
	global_load_dwordx4 v[230:233], v[28:29], off offset:3072
	v_pk_mul_f32 v[16:17], v[16:17], v[26:27] op_sel_hi:[1,0]
	v_pk_mul_f32 v[12:13], v[12:13], v[26:27] op_sel_hi:[1,0]
	s_mov_b32 s0, 0x2ce00000
	v_pk_mul_f32 v[14:15], v[14:15], v[26:27] op_sel_hi:[1,0]
	v_pk_mul_f32 v[8:9], v[8:9], v[26:27] op_sel_hi:[1,0]
	v_pk_mul_f32 v[2:3], v[2:3], v[26:27] op_sel_hi:[1,0]
	s_waitcnt vmcnt(0) lgkmcnt(0)
	v_pk_fma_f32 v[4:5], v[4:5], v[32:33], v[46:47]
	v_pk_fma_f32 v[6:7], v[6:7], v[16:17], v[48:49]
	v_mul_f32_e32 v16, 0xbfb8aa3b, v4
	v_mul_f32_e32 v17, 0xbfb8aa3b, v5
	v_exp_f32_e32 v16, v16
	v_exp_f32_e32 v17, v17
	v_mul_f32_e32 v32, 0xbfb8aa3b, v6
	v_mul_f32_e32 v33, 0xbfb8aa3b, v7
	v_exp_f32_e32 v32, v32
	v_exp_f32_e32 v33, v33
	v_add_f32_e32 v16, 1.0, v16
	v_add_f32_e32 v17, 1.0, v17
	v_rcp_f32_e32 v16, v16
	v_rcp_f32_e32 v17, v17
	v_add_f32_e32 v32, 1.0, v32
	v_add_f32_e32 v33, 1.0, v33
	v_rcp_f32_e32 v32, v32
	v_rcp_f32_e32 v33, v33
	v_pk_mul_f32 v[4:5], v[4:5], v[16:17]
	v_pk_mul_f32 v[16:17], v[30:31], v[26:27] op_sel_hi:[1,0]
	v_pk_fma_f32 v[12:13], v[44:45], v[12:13], v[52:53]
	v_pk_mul_f32 v[6:7], v[6:7], v[32:33]
	v_pk_fma_f32 v[16:17], v[42:43], v[16:17], v[50:51]
	v_mul_f32_e32 v32, 0xbfb8aa3b, v12
	v_mul_f32_e32 v33, 0xbfb8aa3b, v13
	v_mul_f32_e32 v30, 0xbfb8aa3b, v16
	v_mul_f32_e32 v31, 0xbfb8aa3b, v17
	v_exp_f32_e32 v32, v32
	v_exp_f32_e32 v33, v33
	v_exp_f32_e32 v30, v30
	v_exp_f32_e32 v31, v31
	v_add_f32_e32 v32, 1.0, v32
	v_add_f32_e32 v33, 1.0, v33
	v_add_f32_e32 v30, 1.0, v30
	v_add_f32_e32 v31, 1.0, v31
	v_rcp_f32_e32 v32, v32
	v_rcp_f32_e32 v33, v33
	v_rcp_f32_e32 v30, v30
	v_rcp_f32_e32 v31, v31
	v_lshlrev_b32_e32 v58, 16, v54
	v_and_b32_e32 v59, 0xffff0000, v54
	v_lshlrev_b32_e32 v54, 16, v55
	v_and_b32_e32 v55, 0xffff0000, v55
	v_lshlrev_b32_e32 v60, 16, v56
	v_and_b32_e32 v61, 0xffff0000, v56
	v_lshlrev_b32_e32 v56, 16, v57
	v_and_b32_e32 v57, 0xffff0000, v57
	v_pk_mul_f32 v[12:13], v[12:13], v[32:33]
	v_pk_mul_f32 v[6:7], v[6:7], v[54:55]
	v_pk_mul_f32 v[4:5], v[4:5], v[58:59]
	v_pk_mul_f32 v[16:17], v[16:17], v[30:31]
	v_pk_mul_f32 v[12:13], v[12:13], v[56:57]
	v_pk_mul_f32 v[16:17], v[16:17], v[60:61]
	v_cvt_pk_bf16_f32 v4, v4, v5
	v_cvt_pk_bf16_f32 v5, v6, v7
	s_nop 0
	v_cvt_pk_bf16_f32 v6, v16, v17
	v_cvt_pk_bf16_f32 v7, v12, v13
	v_lshl_add_u64 v[12:13], s[10:11], 0, v[20:21]
	v_add_co_u32_e32 v12, vcc, s0, v12
	s_add_u32 s10, s10, 0x4000
	s_nop 0
	v_addc_co_u32_e32 v13, vcc, 0, v13, vcc
	global_store_dwordx4 v[12:13], v[4:7], off
	s_nop 0
	s_nop 0
	s_nop 0
	s_nop 0
	s_nop 0
	s_nop 0
	s_addc_u32 s11, s11, 0
	s_add_u32 s14, s14, 0x38000
	v_add_co_u32_e32 v39, vcc, 8, v39
	s_addc_u32 s15, s15, 0
	s_and_b64 vcc, exec, vcc
	s_nop 0
	v_pk_fma_f32 v[4:5], v[214:215], v[14:15], v[222:223]
	v_pk_fma_f32 v[6:7], v[216:217], v[8:9], v[224:225]
	v_mul_f32_e32 v8, 0xbfb8aa3b, v4
	v_mul_f32_e32 v9, 0xbfb8aa3b, v5
	v_exp_f32_e32 v8, v8
	v_exp_f32_e32 v9, v9
	v_mul_f32_e32 v14, 0xbfb8aa3b, v6
	v_mul_f32_e32 v15, 0xbfb8aa3b, v7
	v_exp_f32_e32 v14, v14
	v_exp_f32_e32 v15, v15
	v_add_f32_e32 v8, 1.0, v8
	v_add_f32_e32 v9, 1.0, v9
	v_rcp_f32_e32 v8, v8
	v_rcp_f32_e32 v9, v9
	v_add_f32_e32 v14, 1.0, v14
	v_add_f32_e32 v15, 1.0, v15
	v_rcp_f32_e32 v14, v14
	v_rcp_f32_e32 v15, v15
	v_pk_mul_f32 v[4:5], v[4:5], v[8:9]
	v_pk_mul_f32 v[8:9], v[10:11], v[26:27] op_sel_hi:[1,0]
	v_pk_fma_f32 v[2:3], v[218:219], v[2:3], v[226:227]
	v_pk_fma_f32 v[8:9], v[220:221], v[8:9], v[228:229]
	v_pk_mul_f32 v[6:7], v[6:7], v[14:15]
	v_mul_f32_e32 v10, 0xbfb8aa3b, v2
	v_mul_f32_e32 v11, 0xbfb8aa3b, v3
	v_mul_f32_e32 v14, 0xbfb8aa3b, v8
	v_mul_f32_e32 v15, 0xbfb8aa3b, v9
	v_exp_f32_e32 v10, v10
	v_exp_f32_e32 v11, v11
	v_exp_f32_e32 v14, v14
	v_exp_f32_e32 v15, v15
	v_add_f32_e32 v10, 1.0, v10
	v_add_f32_e32 v11, 1.0, v11
	v_add_f32_e32 v14, 1.0, v14
	v_add_f32_e32 v15, 1.0, v15
	v_rcp_f32_e32 v10, v10
	v_rcp_f32_e32 v11, v11
	v_rcp_f32_e32 v14, v14
	v_rcp_f32_e32 v15, v15
	v_lshlrev_b32_e32 v16, 16, v230
	v_and_b32_e32 v17, 0xffff0000, v230
	v_lshlrev_b32_e32 v28, 16, v231
	v_and_b32_e32 v29, 0xffff0000, v231
	v_lshlrev_b32_e32 v50, 16, v232
	v_and_b32_e32 v51, 0xffff0000, v232
	v_lshlrev_b32_e32 v52, 16, v233
	v_and_b32_e32 v53, 0xffff0000, v233
	v_pk_mul_f32 v[4:5], v[4:5], v[16:17]
	v_pk_mul_f32 v[2:3], v[2:3], v[10:11]
	v_pk_mul_f32 v[8:9], v[8:9], v[14:15]
	v_pk_mul_f32 v[6:7], v[6:7], v[28:29]
	v_pk_mul_f32 v[8:9], v[8:9], v[52:53]
	v_pk_mul_f32 v[10:11], v[2:3], v[50:51]
	v_cvt_pk_bf16_f32 v2, v4, v5
	v_cvt_pk_bf16_f32 v3, v6, v7
	s_nop 0
	v_cvt_pk_bf16_f32 v4, v10, v11
	v_cvt_pk_bf16_f32 v5, v8, v9
	global_store_dwordx4 v[12:13], v[2:5], off offset:1024
	s_cbranch_vccnz .LBB0_635
	s_branch .LBB0_628

.LBB0_1234:
	global_load_dwordx4 v[2:5], v[22:23], off
	global_load_dwordx4 v[6:9], v[22:23], off offset:1024
	global_load_dwordx4 v[46:49], v[22:23], off offset:2048
	global_load_dwordx4 v[28:31], v[22:23], off offset:3072
	s_waitcnt vmcnt(0)
	v_and_b32_e32 v59, 0xffff0000, v2
	v_lshlrev_b32_e32 v50, 16, v8
	v_and_b32_e32 v51, 0xffff0000, v8
	v_lshlrev_b32_e32 v52, 16, v9
	v_and_b32_e32 v53, 0xffff0000, v9
	v_lshlrev_b32_e32 v9, 16, v2
	v_lshlrev_b32_e32 v8, 16, v4
	v_and_b32_e32 v58, 0xffff0000, v4
	v_lshlrev_b32_e32 v67, 16, v3
	v_lshlrev_b32_e32 v66, 16, v5
	v_and_b32_e32 v69, 0xffff0000, v3
	v_and_b32_e32 v68, 0xffff0000, v5
	v_pk_add_f32 v[2:3], v[8:9], v[58:59]
	v_pk_add_f32 v[4:5], v[66:67], v[68:69]
	v_lshlrev_b32_e32 v55, 16, v7
	v_pk_add_f32 v[2:3], v[2:3], v[4:5]
	v_lshlrev_b32_e32 v54, 16, v6
	v_add_f32_e32 v3, 0, v3
	v_and_b32_e32 v57, 0xffff0000, v7
	v_and_b32_e32 v56, 0xffff0000, v6
	v_add_f32_e32 v43, v2, v3
	v_pk_add_f32 v[2:3], v[54:55], v[56:57]
	v_lshlrev_b32_e32 v38, 16, v46
	v_pk_add_f32 v[2:3], v[2:3], v[2:3] op_sel_hi:[0,1]
	v_and_b32_e32 v44, 0xffff0000, v46
	v_lshlrev_b32_e32 v40, 16, v47
	v_and_b32_e32 v42, 0xffff0000, v47
	v_add_f32_e32 v39, v50, v51
	v_add_f32_e32 v45, v52, v53
	v_mov_b32_e32 v41, v3
	v_pk_add_f32 v[4:5], v[38:39], v[44:45]
	v_pk_add_f32 v[2:3], v[40:41], v[42:43]
	v_lshlrev_b32_e32 v47, 16, v49
	v_lshlrev_b32_e32 v46, 16, v48
	v_and_b32_e32 v49, 0xffff0000, v49
	v_and_b32_e32 v48, 0xffff0000, v48
	v_pk_add_f32 v[2:3], v[4:5], v[2:3]
	v_pk_add_f32 v[4:5], v[46:47], v[48:49]
	v_lshlrev_b32_e32 v32, 16, v28
	v_and_b32_e32 v33, 0xffff0000, v28
	v_lshlrev_b32_e32 v26, 16, v29
	v_and_b32_e32 v27, 0xffff0000, v29
	v_pk_add_f32 v[2:3], v[2:3], v[2:3] op_sel_hi:[0,1]
	v_pk_add_f32 v[4:5], v[4:5], v[4:5] op_sel_hi:[0,1]
	v_lshlrev_b32_e32 v28, 16, v30
	v_and_b32_e32 v36, 0xffff0000, v30
	v_lshlrev_b32_e32 v30, 16, v31
	v_and_b32_e32 v34, 0xffff0000, v31
	v_add_f32_e32 v29, v32, v33
	v_add_f32_e32 v37, v26, v27
	v_mov_b32_e32 v31, v5
	v_mov_b32_e32 v35, v3
	v_pk_add_f32 v[6:7], v[28:29], v[36:37]
	v_pk_add_f32 v[2:3], v[30:31], v[34:35]
	s_nop 0
	v_pk_add_f32 v[2:3], v[6:7], v[2:3]
	s_nop 0
	v_add_f32_e32 v2, v2, v3
	s_waitcnt lgkmcnt(0)
	s_nop 1
	v_add_f32_dpp v2, v2, v2 quad_perm:[1,0,3,2] row_mask:0xf bank_mask:0xf
	s_nop 1
	v_add_f32_dpp v2, v2, v2 quad_perm:[2,3,0,1] row_mask:0xf bank_mask:0xf
	s_nop 1
	v_add_f32_dpp v2, v2, v2 row_half_mirror row_mask:0xf bank_mask:0xf
	s_nop 1
	v_add_f32_dpp v2, v2, v2 row_mirror row_mask:0xf bank_mask:0xf
	s_nop 1
	v_add_f32_dpp v2, v2, v2 row_bcast:15 row_mask:0xa bank_mask:0xf
	s_nop 1
	v_add_f32_dpp v2, v2, v2 row_bcast:31 row_mask:0xc bank_mask:0xf
	s_nop 1
	v_readlane_b32 s100, v2, 63
	v_mov_b32_e32 v29, s100
	v_fmac_f32_e32 v59, 0xba000000, v29
	v_fmac_f32_e32 v9, 0xba000000, v29
	v_fmac_f32_e32 v58, 0xba000000, v29
	v_fmac_f32_e32 v8, 0xba000000, v29
	v_mov_b32_e32 v6, v8
	v_mov_b32_e32 v2, v9
	v_mov_b32_e32 v4, v9
	v_mov_b32_e32 v5, v8
	v_mov_b32_e32 v8, v59
	v_mov_b32_e32 v9, v58
	v_fmac_f32_e32 v69, 0xba000000, v29
	v_fmac_f32_e32 v67, 0xba000000, v29
	v_fmac_f32_e32 v68, 0xba000000, v29
	v_fmac_f32_e32 v66, 0xba000000, v29
	v_pk_mul_f32 v[8:9], v[8:9], v[8:9]
	v_mov_b32_e32 v7, v58
	v_mov_b32_e32 v3, v59
	v_pk_fma_f32 v[58:59], v[4:5], v[4:5], v[8:9]
	v_mov_b32_e32 v8, v66
	v_mov_b32_e32 v4, v67
	v_mov_b32_e32 v70, v67
	v_mov_b32_e32 v71, v66
	v_mov_b32_e32 v66, v69
	v_mov_b32_e32 v67, v68
	v_pk_mul_f32 v[66:67], v[66:67], v[66:67]
	v_fmac_f32_e32 v57, 0xba000000, v29
	v_pk_fma_f32 v[66:67], v[70:71], v[70:71], v[66:67]
	v_fmac_f32_e32 v55, 0xba000000, v29
	v_fmac_f32_e32 v56, 0xba000000, v29
	v_fmac_f32_e32 v54, 0xba000000, v29
	v_mov_b32_e32 v9, v68
	v_mov_b32_e32 v5, v69
	v_pk_add_f32 v[58:59], v[58:59], v[66:67]
	v_mov_b32_e32 v66, v55
	v_mov_b32_e32 v67, v57
	v_mov_b32_e32 v68, v54
	v_mov_b32_e32 v69, v56
	v_pk_add_f32 v[58:59], v[58:59], v[58:59] op_sel_hi:[0,1]
	v_pk_mul_f32 v[66:67], v[66:67], v[66:67]
	v_pk_mul_f32 v[68:69], v[68:69], v[68:69]
	v_fmac_f32_e32 v50, 0xba000000, v29
	v_pk_mov_b32 v[70:71], v[68:69], v[66:67] op_sel:[1,0]
	v_mov_b32_e32 v69, v67
	v_fmac_f32_e32 v52, 0xba000000, v29
	v_fmac_f32_e32 v51, 0xba000000, v29
	v_mul_f32_e32 v58, v50, v50
	v_pk_add_f32 v[66:67], v[70:71], v[68:69]
	v_fmac_f32_e32 v53, 0xba000000, v29
	v_pk_fma_f32 v[68:69], v[50:51], v[50:51], v[58:59] op_sel_hi:[1,1,0]
	v_mul_f32_e32 v58, v52, v52
	v_pk_add_f32 v[66:67], v[66:67], v[66:67] op_sel_hi:[0,1]
	v_pk_fma_f32 v[70:71], v[52:53], v[52:53], v[58:59] op_sel_hi:[1,1,0]
	v_fmac_f32_e32 v42, 0xba000000, v29
	v_fmac_f32_e32 v40, 0xba000000, v29
	v_fmac_f32_e32 v44, 0xba000000, v29
	v_fmac_f32_e32 v38, 0xba000000, v29
	v_mul_f32_e32 v68, v38, v38
	v_mul_f32_e32 v70, v44, v44
	v_mul_f32_e32 v66, v40, v40
	v_mul_f32_e32 v58, v42, v42
	v_pk_add_f32 v[68:69], v[68:69], v[70:71]
	v_pk_add_f32 v[58:59], v[66:67], v[58:59]
	v_fmac_f32_e32 v49, 0xba000000, v29
	v_fmac_f32_e32 v47, 0xba000000, v29
	v_fmac_f32_e32 v48, 0xba000000, v29
	v_fmac_f32_e32 v46, 0xba000000, v29
	v_pk_add_f32 v[58:59], v[68:69], v[58:59]
	v_mov_b32_e32 v66, v47
	v_mov_b32_e32 v67, v49
	v_mov_b32_e32 v68, v46
	v_mov_b32_e32 v69, v48
	v_pk_add_f32 v[58:59], v[58:59], v[58:59] op_sel_hi:[0,1]
	v_pk_mul_f32 v[66:67], v[66:67], v[66:67]
	v_pk_mul_f32 v[68:69], v[68:69], v[68:69]
	v_fmac_f32_e32 v32, 0xba000000, v29
	v_pk_mov_b32 v[70:71], v[68:69], v[66:67] op_sel:[1,0]
	v_mov_b32_e32 v69, v67
	v_fmac_f32_e32 v26, 0xba000000, v29
	v_fmac_f32_e32 v33, 0xba000000, v29
	v_mul_f32_e32 v58, v32, v32
	v_pk_add_f32 v[66:67], v[70:71], v[68:69]
	v_fmac_f32_e32 v27, 0xba000000, v29
	v_pk_fma_f32 v[68:69], v[32:33], v[32:33], v[58:59] op_sel_hi:[1,1,0]
	v_mul_f32_e32 v58, v26, v26
	v_pk_add_f32 v[66:67], v[66:67], v[66:67] op_sel_hi:[0,1]
	v_pk_fma_f32 v[70:71], v[26:27], v[26:27], v[58:59] op_sel_hi:[1,1,0]
	v_fmac_f32_e32 v34, 0xba000000, v29
	v_fmac_f32_e32 v30, 0xba000000, v29
	v_fmac_f32_e32 v36, 0xba000000, v29
	v_fmac_f32_e32 v28, 0xba000000, v29
	v_mul_f32_e32 v68, v28, v28
	v_mul_f32_e32 v70, v36, v36
	v_mul_f32_e32 v66, v30, v30
	v_mul_f32_e32 v58, v34, v34
	v_pk_add_f32 v[68:69], v[68:69], v[70:71]
	v_pk_add_f32 v[58:59], v[66:67], v[58:59]
	s_nop 0
	v_pk_add_f32 v[58:59], v[68:69], v[58:59]
	s_nop 0
	v_add_f32_e32 v29, v58, v59
	s_waitcnt lgkmcnt(0)
	s_nop 1
	v_add_f32_dpp v29, v29, v29 quad_perm:[1,0,3,2] row_mask:0xf bank_mask:0xf
	s_nop 1
	v_add_f32_dpp v29, v29, v29 quad_perm:[2,3,0,1] row_mask:0xf bank_mask:0xf
	s_nop 1
	v_add_f32_dpp v29, v29, v29 row_half_mirror row_mask:0xf bank_mask:0xf
	s_nop 1
	v_add_f32_dpp v29, v29, v29 row_mirror row_mask:0xf bank_mask:0xf
	s_nop 1
	v_add_f32_dpp v29, v29, v29 row_bcast:15 row_mask:0xa bank_mask:0xf
	s_nop 1
	v_add_f32_dpp v29, v29, v29 row_bcast:31 row_mask:0xc bank_mask:0xf
	s_nop 1
	v_readlane_b32 s100, v29, 63
	v_mov_b32_e32 v29, s100
	v_fmamk_f32 v29, v29, 0x3a000000, v171
	v_cmp_gt_f32_e32 vcc, s9, v29
	v_mul_f32_e32 v31, 0x4f800000, v29
	s_nop 0
	v_cndmask_b32_e32 v29, v29, v31, vcc
	v_sqrt_f32_e32 v31, v29
	s_nop 0
	v_add_u32_e32 v35, -1, v31
	v_fma_f32 v37, -v35, v31, v29
	v_cmp_ge_f32_e64 s[0:1], 0, v37
	v_add_u32_e32 v37, 1, v31
	s_nop 0
	v_cndmask_b32_e64 v35, v31, v35, s[0:1]
	v_fma_f32 v31, -v37, v31, v29
	v_cmp_lt_f32_e64 s[0:1], 0, v31
	s_nop 1
	v_cndmask_b32_e64 v31, v35, v37, s[0:1]
	v_mul_f32_e32 v35, 0x37800000, v31
	v_cndmask_b32_e32 v31, v31, v35, vcc
	v_cmp_class_f32_e32 vcc, v29, v200
	s_nop 1
	v_cndmask_b32_e32 v29, v31, v29, vcc
	v_div_scale_f32 v31, s[0:1], v29, v29, 1.0
	v_rcp_f32_e32 v35, v31
	s_mov_b64 s[0:1], -1
	v_fma_f32 v37, -v31, v35, 1.0
	v_fmac_f32_e32 v35, v37, v35
	v_div_scale_f32 v37, vcc, 1.0, v29, 1.0
	v_mul_f32_e32 v39, v37, v35
	v_fma_f32 v41, -v31, v39, v37
	v_fmac_f32_e32 v39, v41, v35
	v_fma_f32 v31, -v31, v39, v37
	v_div_fmas_f32 v31, v31, v35, v39
	v_div_fixup_f32 v58, v31, v29, 1.0
	v_pk_mul_f32 v[70:71], v[2:3], v[58:59] op_sel_hi:[1,0]
	v_pk_mul_f32 v[72:73], v[4:5], v[58:59] op_sel_hi:[1,0]
	flat_load_dwordx4 v[2:5], v[10:11]
	flat_load_dwordx4 v[66:69], v[12:13]
	v_pk_mul_f32 v[6:7], v[6:7], v[58:59] op_sel_hi:[1,0]
	v_pk_mul_f32 v[8:9], v[8:9], v[58:59] op_sel_hi:[1,0]
	s_and_b64 vcc, exec, s[10:11]
	s_waitcnt vmcnt(0) lgkmcnt(0)
	v_pk_fma_f32 v[4:5], v[4:5], v[72:73], v[68:69]
	v_pk_fma_f32 v[2:3], v[2:3], v[70:71], v[66:67]
	flat_load_dwordx4 v[66:69], v[10:11] offset:16
	flat_load_dwordx4 v[70:73], v[12:13] offset:16
	s_waitcnt vmcnt(0) lgkmcnt(0)
	v_pk_fma_f32 v[8:9], v[68:69], v[8:9], v[72:73]
	v_pk_fma_f32 v[6:7], v[66:67], v[6:7], v[70:71]
	s_cbranch_vccz .LBB0_1236
	v_add_co_u32_e32 v70, vcc, 0xd8900000, v22
	v_cvt_pk_bf16_f32 v66, v2, v3
	v_cvt_pk_bf16_f32 v67, v4, v5
	v_cvt_pk_bf16_f32 v68, v6, v7
	v_cvt_pk_bf16_f32 v69, v8, v9
	s_nop 1
	v_addc_co_u32_e32 v71, vcc, -1, v23, vcc
	global_store_dwordx4 v[70:71], v[66:69], off
	s_mov_b64 s[0:1], 0

	.amdhsa_kernel _Z8mega_fwd4Args
		.amdhsa_group_segment_fixed_size 0
		.amdhsa_private_segment_fixed_size 0
		.amdhsa_kernarg_size 568
		.amdhsa_user_sgpr_count 2
		.amdhsa_user_sgpr_dispatch_ptr 0
		.amdhsa_user_sgpr_queue_ptr 0
		.amdhsa_user_sgpr_kernarg_segment_ptr 1
		.amdhsa_user_sgpr_dispatch_id 0
		.amdhsa_user_sgpr_kernarg_preload_length 0
		.amdhsa_user_sgpr_kernarg_preload_offset 0
		.amdhsa_user_sgpr_private_segment_size 0
		.amdhsa_uses_dynamic_stack 0
		.amdhsa_enable_private_segment 0
		.amdhsa_system_sgpr_workgroup_id_x 1
		.amdhsa_system_sgpr_workgroup_id_y 0
		.amdhsa_system_sgpr_workgroup_id_z 0
		.amdhsa_system_sgpr_workgroup_info 0
		.amdhsa_system_vgpr_workitem_id 0
		.amdhsa_next_free_vgpr 246
		.amdhsa_next_free_sgpr 102
		.amdhsa_accum_offset 248
		.amdhsa_reserve_vcc 1
		.amdhsa_float_round_mode_32 0
		.amdhsa_float_round_mode_16_64 0
		.amdhsa_float_denorm_mode_32 3
		.amdhsa_float_denorm_mode_16_64 3
		.amdhsa_dx10_clamp 1
		.amdhsa_ieee_mode 1
		.amdhsa_fp16_overflow 0
		.amdhsa_tg_split 0
		.amdhsa_exception_fp_ieee_invalid_op 0
		.amdhsa_exception_fp_denorm_src 0
		.amdhsa_exception_fp_ieee_div_zero 0
		.amdhsa_exception_fp_ieee_overflow 0
		.amdhsa_exception_fp_ieee_underflow 0
		.amdhsa_exception_fp_ieee_inexact 0
		.amdhsa_exception_int_div_zero 0
	.end_amdhsa_kernel

amdhsa.kernels:
  - .agpr_count:     0
    .args:
      - .offset:         0
        .size:           312
        .value_kind:     by_value
      - .offset:         312
        .size:           4
        .value_kind:     hidden_block_count_x
      - .offset:         316
        .size:           4
        .value_kind:     hidden_block_count_y
      - .offset:         320
        .size:           4
        .value_kind:     hidden_block_count_z
      - .offset:         324
        .size:           2
        .value_kind:     hidden_group_size_x
      - .offset:         326
        .size:           2
        .value_kind:     hidden_group_size_y
      - .offset:         328
        .size:           2
        .value_kind:     hidden_group_size_z
      - .offset:         330
        .size:           2
        .value_kind:     hidden_remainder_x
      - .offset:         332
        .size:           2
        .value_kind:     hidden_remainder_y
      - .offset:         334
        .size:           2
        .value_kind:     hidden_remainder_z
      - .offset:         352
        .size:           8
        .value_kind:     hidden_global_offset_x
      - .offset:         360
        .size:           8
        .value_kind:     hidden_global_offset_y
      - .offset:         368
        .size:           8
        .value_kind:     hidden_global_offset_z
      - .offset:         376
        .size:           2
        .value_kind:     hidden_grid_dims
      - .offset:         432
        .size:           4
        .value_kind:     hidden_dynamic_lds_size
    .group_segment_fixed_size: 0
    .kernarg_segment_align: 8
    .kernarg_segment_size: 568
    .language:       OpenCL C
    .language_version:
      - 2
      - 0
    .max_flat_workgroup_size: 512
    .name:           _Z8mega_fwd4Args
    .private_segment_fixed_size: 0
    .sgpr_count:     108
    .sgpr_spill_count: 503
    .symbol:         _Z8mega_fwd4Args.kd
    .uniform_work_group_size: 1
    .uses_dynamic_stack: false
    .vgpr_count:     246
    .vgpr_spill_count: 0
    .wavefront_size: 64
